# rebal1: stack4 + attention steady loop step 1: row-sum adds re-balanced over MFMA gaps (3 adds + 2 cvt per QK gap, 9 adds into exp-only PV gaps)
# baseline (speedup 1.0000x reference)
.LBB0_413:
	s_mov_b32 s16, s26
	s_mov_b32 s2, s18
	s_mov_b32 s3, s24
	v_lshl_add_u32 v69, s17, 1, v232
	ds_read_b64_tr_b16 v[76:77], v69 offset:24576
	ds_read_b64_tr_b16 v[78:79], v69 offset:25088
	v_add_f32_e32 v255, v100, v101
	v_add_f32_e32 v255, v102, v255
	v_add_f32_e32 v255, v103, v255
	v_cvt_pk_bf16_f32 v160, v100, v101
	v_cvt_pk_bf16_f32 v161, v102, v103
	s_waitcnt lgkmcnt(9)
	v_mfma_f32_32x32x16_bf16 v[132:147], v[208:211], v[176:179], 0
	v_add_f32_e32 v255, v84, v255
	v_add_f32_e32 v255, v85, v255
	v_add_f32_e32 v255, v86, v255
	v_cvt_pk_bf16_f32 v162, v104, v105
	v_cvt_pk_bf16_f32 v163, v106, v107
	s_waitcnt lgkmcnt(8)
	v_mfma_f32_32x32x16_bf16 v[116:131], v[200:203], v[176:179], 0
	ds_read_b64_tr_b16 v[80:81], v69 offset:25600
	ds_read_b64_tr_b16 v[82:83], v69 offset:26112
	v_add_f32_e32 v255, v87, v255
	v_add_f32_e32 v255, v88, v255
	v_add_f32_e32 v255, v89, v255
	v_cvt_pk_bf16_f32 v156, v108, v109
	v_cvt_pk_bf16_f32 v157, v110, v111
	s_waitcnt lgkmcnt(9)
	v_mfma_f32_32x32x16_bf16 v[132:147], v[204:207], v[172:175], v[132:147]
	v_add_f32_e32 v255, v90, v255
	v_add_f32_e32 v255, v91, v255
	v_add_f32_e32 v255, v92, v255
	v_cvt_pk_bf16_f32 v158, v112, v113
	v_cvt_pk_bf16_f32 v159, v114, v115
	s_waitcnt lgkmcnt(8)
	v_mfma_f32_32x32x16_bf16 v[116:131], v[196:199], v[172:175], v[116:131]
	ds_read_b64_tr_b16 v[100:101], v69 offset:26624
	ds_read_b64_tr_b16 v[102:103], v69 offset:27136
	v_add_f32_e32 v255, v93, v255
	v_add_f32_e32 v255, v94, v255
	v_add_f32_e32 v255, v95, v255
	v_cvt_pk_bf16_f32 v152, v84, v85
	v_cvt_pk_bf16_f32 v153, v86, v87
	s_waitcnt lgkmcnt(9)
	v_mfma_f32_32x32x16_bf16 v[132:147], v[192:195], v[168:171], v[132:147]
	v_add_f32_e32 v255, v96, v255
	v_add_f32_e32 v255, v97, v255
	v_add_f32_e32 v255, v98, v255
	v_cvt_pk_bf16_f32 v154, v88, v89
	v_cvt_pk_bf16_f32 v155, v90, v91
	s_waitcnt lgkmcnt(8)
	v_mfma_f32_32x32x16_bf16 v[116:131], v[188:191], v[168:171], v[116:131]
	ds_read_b64_tr_b16 v[84:85], v69 offset:27648
	ds_read_b64_tr_b16 v[86:87], v69 offset:28160
	v_add_f32_e32 v255, v99, v255
	v_add_f32_e32 v255, v104, v255
	v_add_f32_e32 v255, v105, v255
	v_cvt_pk_bf16_f32 v148, v92, v93
	v_cvt_pk_bf16_f32 v149, v94, v95
	s_waitcnt lgkmcnt(9)
	v_mfma_f32_32x32x16_bf16 v[132:147], v[184:187], v[164:167], v[132:147]
	v_add_f32_e32 v255, v106, v255
	v_add_f32_e32 v255, v107, v255
	v_cvt_pk_bf16_f32 v150, v96, v97
	v_cvt_pk_bf16_f32 v151, v98, v99
	s_waitcnt lgkmcnt(8)
	v_mfma_f32_32x32x16_bf16 v[116:131], v[180:183], v[164:167], v[116:131]
	v_lshl_add_u64 v[74:75], v[0:1], 0, s[14:15]
	s_add_i32 m0, s24, s0
	v_lshl_add_u64 v[72:73], v[74:75], 0, s[76:77]
	global_load_lds_dwordx4 v[72:73], off
	s_lshl_b32 s17, s26, 1
	s_add_i32 s17, s17, s1
	s_mov_b32 m0, s17
	v_lshl_add_u64 v[72:73], v[70:71], 0, s[14:15]
	v_lshl_add_u64 v[88:89], v[72:73], 0, s[90:91]
	global_load_lds_dwordx4 v[88:89], off
	s_add_i32 m0, s17, 0x2000
	v_lshl_add_u64 v[88:89], v[72:73], 0, s[92:93]
	global_load_lds_dwordx4 v[88:89], off
	s_waitcnt lgkmcnt(6)
	v_mfma_f32_32x32x16_bf16 v[36:51], v[160:163], v[76:79], v[36:51]
	v_exp_f32_e32 v132, v132
	v_exp_f32_e32 v133, v133
	v_add_f32_e32 v254, v108, v109
	ds_read_b64_tr_b16 v[76:77], v69 offset:28672
	ds_read_b64_tr_b16 v[78:79], v69 offset:29184
	s_waitcnt lgkmcnt(6)
	v_mfma_f32_32x32x16_bf16 v[36:51], v[156:159], v[80:83], v[36:51]
	v_exp_f32_e32 v134, v134
	v_exp_f32_e32 v135, v135
	v_add_f32_e32 v254, v110, v254
	ds_read_b64_tr_b16 v[80:81], v69 offset:29696
	ds_read_b64_tr_b16 v[82:83], v69 offset:30208
	s_waitcnt lgkmcnt(6)
	v_mfma_f32_32x32x16_bf16 v[36:51], v[152:155], v[100:103], v[36:51]
	v_exp_f32_e32 v136, v136
	v_exp_f32_e32 v137, v137
	v_add_f32_e32 v254, v111, v254
	ds_read_b64_tr_b16 v[88:89], v69 offset:30720
	ds_read_b64_tr_b16 v[90:91], v69 offset:31232
	s_waitcnt lgkmcnt(6)
	v_mfma_f32_32x32x16_bf16 v[36:51], v[148:151], v[84:87], v[36:51]
	v_exp_f32_e32 v138, v138
	v_exp_f32_e32 v139, v139
	v_add_f32_e32 v254, v112, v254
	ds_read_b64_tr_b16 v[84:85], v69 offset:31744
	ds_read_b64_tr_b16 v[86:87], v69 offset:32256
	s_waitcnt lgkmcnt(6)
	v_mfma_f32_32x32x16_bf16 v[52:67], v[160:163], v[76:79], v[52:67]
	v_exp_f32_e32 v140, v140
	v_exp_f32_e32 v141, v141
	v_add_f32_e32 v254, v113, v254
	ds_read_b64_tr_b16 v[76:77], v69 offset:32768
	ds_read_b64_tr_b16 v[78:79], v69 offset:33280
	s_waitcnt lgkmcnt(6)
	v_mfma_f32_32x32x16_bf16 v[52:67], v[156:159], v[80:83], v[52:67]
	v_exp_f32_e32 v142, v142
	v_exp_f32_e32 v143, v143
	v_add_f32_e32 v254, v114, v254
	ds_read_b64_tr_b16 v[80:81], v69 offset:33792
	ds_read_b64_tr_b16 v[82:83], v69 offset:34304
	s_waitcnt lgkmcnt(6)
	v_mfma_f32_32x32x16_bf16 v[52:67], v[152:155], v[88:91], v[52:67]
	v_exp_f32_e32 v144, v144
	v_exp_f32_e32 v145, v145
	v_add_f32_e32 v254, v115, v254
	ds_read_b64_tr_b16 v[88:89], v69 offset:34816
	ds_read_b64_tr_b16 v[90:91], v69 offset:35328
	s_waitcnt lgkmcnt(6)
	v_mfma_f32_32x32x16_bf16 v[52:67], v[148:151], v[84:87], v[52:67]
	v_exp_f32_e32 v146, v146
	v_exp_f32_e32 v147, v147
	v_add_f32_e32 v255, v254, v255
	ds_read_b64_tr_b16 v[84:85], v69 offset:35840
	ds_read_b64_tr_b16 v[86:87], v69 offset:36352
	s_waitcnt lgkmcnt(6)
	v_mfma_f32_32x32x16_bf16 v[4:19], v[160:163], v[76:79], v[4:19]
	v_exp_f32_e32 v116, v116
	v_exp_f32_e32 v117, v117
	v_add_f32_e32 v68, v68, v255
	ds_read_b64_tr_b16 v[76:77], v69 offset:36864
	ds_read_b64_tr_b16 v[78:79], v69 offset:37376
	s_waitcnt lgkmcnt(6)
	v_mfma_f32_32x32x16_bf16 v[4:19], v[156:159], v[80:83], v[4:19]
	v_exp_f32_e32 v118, v118
	v_exp_f32_e32 v119, v119
	ds_read_b64_tr_b16 v[80:81], v69 offset:37888
	ds_read_b64_tr_b16 v[82:83], v69 offset:38400
	s_waitcnt lgkmcnt(6)
	v_mfma_f32_32x32x16_bf16 v[4:19], v[152:155], v[88:91], v[4:19]
	v_exp_f32_e32 v120, v120
	v_exp_f32_e32 v121, v121
	ds_read_b64_tr_b16 v[88:89], v69 offset:38912
	ds_read_b64_tr_b16 v[90:91], v69 offset:39424
	s_waitcnt lgkmcnt(6)
	v_mfma_f32_32x32x16_bf16 v[4:19], v[148:151], v[84:87], v[4:19]
	v_exp_f32_e32 v122, v122
	v_exp_f32_e32 v123, v123
	ds_read_b64_tr_b16 v[84:85], v69 offset:39936
	ds_read_b64_tr_b16 v[86:87], v69 offset:40448
	v_add_u32_e32 v69, s16, v230
	ds_read_b128 v[92:95], v69
	ds_read_b128 v[96:99], v69 offset:512
	s_waitcnt lgkmcnt(8)
	v_mfma_f32_32x32x16_bf16 v[20:35], v[160:163], v[76:79], v[20:35]
	v_exp_f32_e32 v124, v124
	v_exp_f32_e32 v125, v125
	ds_read_b128 v[76:79], v69 offset:2048
	ds_read_b128 v[180:183], v69 offset:2560
	s_waitcnt lgkmcnt(8)
	v_mfma_f32_32x32x16_bf16 v[20:35], v[156:159], v[80:83], v[20:35]
	v_exp_f32_e32 v126, v126
	v_exp_f32_e32 v127, v127
	ds_read_b128 v[80:83], v69 offset:4096
	ds_read_b128 v[184:187], v69 offset:4608
	ds_read_b128 v[188:191], v69 offset:6144
	ds_read_b128 v[192:195], v69 offset:6656
	s_waitcnt lgkmcnt(10)
	v_mfma_f32_32x32x16_bf16 v[20:35], v[152:155], v[88:91], v[20:35]
	v_exp_f32_e32 v128, v128
	v_exp_f32_e32 v129, v129
	s_waitcnt lgkmcnt(8)
	v_mfma_f32_32x32x16_bf16 v[20:35], v[148:151], v[84:87], v[20:35]
	v_exp_f32_e32 v130, v130
	v_exp_f32_e32 v131, v131
	s_add_i32 s17, s26, 0x2000
	s_cmpk_lg_i32 s26, 0x4000
	s_cselect_b32 s24, s17, 0
	v_lshl_add_u32 v69, s3, 1, v232
	s_waitcnt vmcnt(3) lgkmcnt(0)
	s_barrier
	ds_read_b64_tr_b16 v[196:197], v69 offset:24576
	ds_read_b64_tr_b16 v[198:199], v69 offset:25088
	s_waitcnt lgkmcnt(9)
	v_mfma_f32_32x32x16_bf16 v[100:115], v[92:95], v[176:179], 0
	v_add_f32_e32 v84, v132, v133
	v_add_f32_e32 v84, v134, v84
	v_add_f32_e32 v84, v135, v84
	v_add_f32_e32 v84, v136, v84
	v_add_f32_e32 v84, v137, v84
	v_cvt_pk_bf16_f32 v160, v132, v133
	v_cvt_pk_bf16_f32 v161, v134, v135
	v_add_f32_e32 v84, v138, v84
	v_add_f32_e32 v84, v139, v84
	v_add_f32_e32 v84, v140, v84
	v_add_f32_e32 v148, v141, v84
	s_waitcnt lgkmcnt(8)
	v_mfma_f32_32x32x16_bf16 v[84:99], v[96:99], v[176:179], 0
	v_cvt_pk_bf16_f32 v162, v136, v137
	v_cvt_pk_bf16_f32 v163, v138, v139
	ds_read_b64_tr_b16 v[132:133], v69 offset:25600
	ds_read_b64_tr_b16 v[134:135], v69 offset:26112
	s_waitcnt lgkmcnt(9)
	v_mfma_f32_32x32x16_bf16 v[100:115], v[76:79], v[172:175], v[100:115]
	v_add_f32_e32 v76, v142, v148
	v_add_f32_e32 v76, v143, v76
	v_add_f32_e32 v76, v144, v76
	v_add_f32_e32 v76, v145, v76
	v_cvt_pk_bf16_f32 v156, v140, v141
	v_cvt_pk_bf16_f32 v157, v142, v143
	s_waitcnt lgkmcnt(8)
	v_mfma_f32_32x32x16_bf16 v[84:99], v[180:183], v[172:175], v[84:99]
	v_add_f32_e32 v76, v146, v76
	v_add_f32_e32 v76, v147, v76
	v_add_f32_e32 v76, v116, v76
	v_add_f32_e32 v136, v117, v76
	v_cvt_pk_bf16_f32 v158, v144, v145
	v_cvt_pk_bf16_f32 v159, v146, v147
	ds_read_b64_tr_b16 v[76:77], v69 offset:26624
	ds_read_b64_tr_b16 v[78:79], v69 offset:27136
	s_waitcnt lgkmcnt(9)
	v_mfma_f32_32x32x16_bf16 v[100:115], v[80:83], v[168:171], v[100:115]
	v_add_f32_e32 v80, v118, v136
	v_add_f32_e32 v80, v119, v80
	v_add_f32_e32 v80, v120, v80
	v_add_f32_e32 v80, v121, v80
	v_cvt_pk_bf16_f32 v152, v116, v117
	v_cvt_pk_bf16_f32 v153, v118, v119
	s_waitcnt lgkmcnt(8)
	v_mfma_f32_32x32x16_bf16 v[84:99], v[184:187], v[168:171], v[84:99]
	v_add_f32_e32 v80, v122, v80
	v_add_f32_e32 v80, v123, v80
	v_add_f32_e32 v80, v124, v80
	v_add_f32_e32 v116, v125, v80
	v_cvt_pk_bf16_f32 v154, v120, v121
	v_cvt_pk_bf16_f32 v155, v122, v123
	ds_read_b64_tr_b16 v[80:81], v69 offset:27648
	ds_read_b64_tr_b16 v[82:83], v69 offset:28160
	s_waitcnt lgkmcnt(9)
	v_mfma_f32_32x32x16_bf16 v[100:115], v[188:191], v[164:167], v[100:115]
	v_add_f32_e32 v116, v126, v116
	v_add_f32_e32 v116, v127, v116
	v_add_f32_e32 v116, v128, v116
	v_add_f32_e32 v116, v129, v116
	v_cvt_pk_bf16_f32 v148, v124, v125
	v_cvt_pk_bf16_f32 v149, v126, v127
	s_waitcnt lgkmcnt(8)
	v_mfma_f32_32x32x16_bf16 v[84:99], v[192:195], v[164:167], v[84:99]
	v_add_f32_e32 v116, v130, v116
	v_add_f32_e32 v116, v131, v116
	v_add_f32_e32 v116, 0, v116
	v_cvt_pk_bf16_f32 v150, v128, v129
	v_cvt_pk_bf16_f32 v151, v130, v131
	s_add_i32 m0, s26, s0
	v_lshl_add_u64 v[74:75], v[74:75], 0, s[28:29]
	global_load_lds_dwordx4 v[74:75], off
	s_lshl_b32 s3, s24, 1
	s_add_i32 s3, s3, s1
	s_mov_b32 m0, s3
	v_lshl_add_u64 v[74:75], v[72:73], 0, s[66:67]
	global_load_lds_dwordx4 v[74:75], off
	s_add_i32 m0, s3, 0x2000
	v_lshl_add_u64 v[72:73], v[72:73], 0, s[72:73]
	global_load_lds_dwordx4 v[72:73], off
	v_add_f32_e32 v68, v68, v116
	s_waitcnt lgkmcnt(6)
	v_mfma_f32_32x32x16_bf16 v[36:51], v[160:163], v[196:199], v[36:51]
	v_exp_f32_e32 v100, v100
	v_exp_f32_e32 v101, v101
	ds_read_b64_tr_b16 v[72:73], v69 offset:28672
	ds_read_b64_tr_b16 v[74:75], v69 offset:29184
	s_waitcnt lgkmcnt(6)
	v_mfma_f32_32x32x16_bf16 v[36:51], v[156:159], v[132:135], v[36:51]
	v_exp_f32_e32 v102, v102
	v_exp_f32_e32 v103, v103
	ds_read_b64_tr_b16 v[116:117], v69 offset:29696
	ds_read_b64_tr_b16 v[118:119], v69 offset:30208
	s_waitcnt lgkmcnt(6)
	v_mfma_f32_32x32x16_bf16 v[36:51], v[152:155], v[76:79], v[36:51]
	v_exp_f32_e32 v104, v104
	v_exp_f32_e32 v105, v105
	ds_read_b64_tr_b16 v[76:77], v69 offset:30720
	ds_read_b64_tr_b16 v[78:79], v69 offset:31232
	s_waitcnt lgkmcnt(6)
	v_mfma_f32_32x32x16_bf16 v[36:51], v[148:151], v[80:83], v[36:51]
	v_exp_f32_e32 v106, v106
	v_exp_f32_e32 v107, v107
	ds_read_b64_tr_b16 v[80:81], v69 offset:31744
	ds_read_b64_tr_b16 v[82:83], v69 offset:32256
	s_waitcnt lgkmcnt(6)
	v_mfma_f32_32x32x16_bf16 v[52:67], v[160:163], v[72:75], v[52:67]
	v_exp_f32_e32 v108, v108
	v_exp_f32_e32 v109, v109
	ds_read_b64_tr_b16 v[72:73], v69 offset:32768
	ds_read_b64_tr_b16 v[74:75], v69 offset:33280
	s_waitcnt lgkmcnt(6)
	v_mfma_f32_32x32x16_bf16 v[52:67], v[156:159], v[116:119], v[52:67]
	v_exp_f32_e32 v110, v110
	v_exp_f32_e32 v111, v111
	ds_read_b64_tr_b16 v[116:117], v69 offset:33792
	ds_read_b64_tr_b16 v[118:119], v69 offset:34304
	s_waitcnt lgkmcnt(6)
	v_mfma_f32_32x32x16_bf16 v[52:67], v[152:155], v[76:79], v[52:67]
	v_exp_f32_e32 v112, v112
	v_exp_f32_e32 v113, v113
	ds_read_b64_tr_b16 v[76:77], v69 offset:34816
	ds_read_b64_tr_b16 v[78:79], v69 offset:35328
	s_waitcnt lgkmcnt(6)
	v_mfma_f32_32x32x16_bf16 v[52:67], v[148:151], v[80:83], v[52:67]
	v_exp_f32_e32 v114, v114
	v_exp_f32_e32 v115, v115
	ds_read_b64_tr_b16 v[80:81], v69 offset:35840
	ds_read_b64_tr_b16 v[82:83], v69 offset:36352
	s_waitcnt lgkmcnt(6)
	v_mfma_f32_32x32x16_bf16 v[4:19], v[160:163], v[72:75], v[4:19]
	v_exp_f32_e32 v84, v84
	v_exp_f32_e32 v85, v85
	ds_read_b64_tr_b16 v[72:73], v69 offset:36864
	ds_read_b64_tr_b16 v[74:75], v69 offset:37376
	s_waitcnt lgkmcnt(6)
	v_mfma_f32_32x32x16_bf16 v[4:19], v[156:159], v[116:119], v[4:19]
	v_exp_f32_e32 v86, v86
	v_exp_f32_e32 v87, v87
	ds_read_b64_tr_b16 v[116:117], v69 offset:37888
	ds_read_b64_tr_b16 v[118:119], v69 offset:38400
	s_waitcnt lgkmcnt(6)
	v_mfma_f32_32x32x16_bf16 v[4:19], v[152:155], v[76:79], v[4:19]
	v_exp_f32_e32 v88, v88
	v_exp_f32_e32 v89, v89
	ds_read_b64_tr_b16 v[76:77], v69 offset:38912
	ds_read_b64_tr_b16 v[78:79], v69 offset:39424
	s_waitcnt lgkmcnt(6)
	v_mfma_f32_32x32x16_bf16 v[4:19], v[148:151], v[80:83], v[4:19]
	v_exp_f32_e32 v90, v90
	v_exp_f32_e32 v91, v91
	ds_read_b64_tr_b16 v[80:81], v69 offset:39936
	ds_read_b64_tr_b16 v[82:83], v69 offset:40448
	v_add_u32_e32 v69, s24, v230
	ds_read_b128 v[208:211], v69
	ds_read_b128 v[200:203], v69 offset:512
	s_waitcnt lgkmcnt(8)
	v_mfma_f32_32x32x16_bf16 v[20:35], v[160:163], v[72:75], v[20:35]
	v_exp_f32_e32 v92, v92
	v_exp_f32_e32 v93, v93
	ds_read_b128 v[204:207], v69 offset:2048
	ds_read_b128 v[196:199], v69 offset:2560
	s_waitcnt lgkmcnt(8)
	v_mfma_f32_32x32x16_bf16 v[20:35], v[156:159], v[116:119], v[20:35]
	v_exp_f32_e32 v94, v94
	v_exp_f32_e32 v95, v95
	ds_read_b128 v[192:195], v69 offset:4096
	ds_read_b128 v[188:191], v69 offset:4608
	ds_read_b128 v[184:187], v69 offset:6144
	ds_read_b128 v[180:183], v69 offset:6656
	s_waitcnt lgkmcnt(10)
	v_mfma_f32_32x32x16_bf16 v[20:35], v[152:155], v[76:79], v[20:35]
	v_exp_f32_e32 v96, v96
	v_exp_f32_e32 v97, v97
	s_waitcnt lgkmcnt(8)
	v_mfma_f32_32x32x16_bf16 v[20:35], v[148:151], v[80:83], v[20:35]
	v_exp_f32_e32 v98, v98
	v_exp_f32_e32 v99, v99
	s_add_i32 s3, s24, 0x2000
	s_cmpk_lg_i32 s24, 0x4000
	s_cselect_b32 s26, s3, 0
	s_add_i32 s18, s2, 2
	s_add_u32 s14, s14, 0x20000
	s_addc_u32 s15, s15, 0
	s_mov_b32 s17, s16
	s_cmp_ge_u32 s18, s21
	s_waitcnt vmcnt(3) lgkmcnt(0)
	s_barrier
	s_cbranch_scc0 .LBB0_413
	s_add_i32 s64, s2, -3
	s_lshl_b64 s[12:13], s[12:13], 9
	s_add_i32 s2, s64, 1
	s_cmp_lt_u32 s2, s21
	s_cbranch_scc0 .LBB0_441
